# speedup vs baseline: 1.0104x; 1.0027x over previous
; DI float h2lo(unsigned u) { return (float)__builtin_bit_cast(f16x2_t, u)[0]; }
; DI float h2hi(unsigned u) { return (float)__builtin_bit_cast(f16x2_t, u)[1]; }
; DI float shfl_xor_l(float v, int mask, int lane) { return __int_as_float(__builtin_amdgcn_ds_bpermute((lane ^ mask) << 2, __float_as_int(v))); }
; DI void ln_phase(const Params& p, const u16* src, const float* g, const float* b, float* dstf, u16* dstb) {
;     ...
;     for (int i = 0; i < 4; ++i) { v[i] = (f32x4){h2lo(raw[i][0]), h2hi(raw[i][0]), h2lo(raw[i][1]), h2hi(raw[i][1])}; s += (v[i][0] + v[i][1]) + (v[i][2] + v[i][3]); }
; #pragma unroll
;     for (int o = 32; o >= 1; o >>= 1) s += shfl_xor_l(s, o, lane);
;     const float mu = s * (1.0f / 1024.0f);
;     float q = 0.f;
; #pragma unroll
;     for (int i = 0; i < 4; ++i) { v[i] = v[i] - mu; q += (v[i][0] * v[i][0] + v[i][1] * v[i][1]) + (v[i][2] * v[i][2] + v[i][3] * v[i][3]); }
; #pragma unroll
;     for (int o = 32; o >= 1; o >>= 1) q += shfl_xor_l(q, o, lane);
.LBB0_1111:
	s_or_b64 exec, exec, s[28:29]
	s_waitcnt vmcnt(3)
	v_cvt_f32_f16_sdwa v60, v52 dst_sel:DWORD dst_unused:UNUSED_PAD src0_sel:WORD_1
	v_cvt_f32_f16_e32 v62, v52
	v_cvt_f32_f16_sdwa v61, v53 dst_sel:DWORD dst_unused:UNUSED_PAD src0_sel:WORD_1
	v_cvt_f32_f16_e32 v63, v53
	s_waitcnt vmcnt(2)
	v_cvt_f32_f16_e32 v66, v50
	v_cvt_f32_f16_e32 v67, v51
	s_waitcnt vmcnt(0)
	v_cvt_f32_f16_sdwa v68, v46 dst_sel:DWORD dst_unused:UNUSED_PAD src0_sel:WORD_1
	v_pk_add_f32 v[60:61], v[62:63], v[60:61]
	v_cvt_f32_f16_sdwa v62, v50 dst_sel:DWORD dst_unused:UNUSED_PAD src0_sel:WORD_1
	v_cvt_f32_f16_sdwa v63, v51 dst_sel:DWORD dst_unused:UNUSED_PAD src0_sel:WORD_1
	v_add_f32_e32 v59, v60, v61
	v_add_f32_e32 v61, 0, v59
	v_cvt_f32_f16_sdwa v59, v48 dst_sel:DWORD dst_unused:UNUSED_PAD src0_sel:WORD_1
	v_pk_add_f32 v[62:63], v[66:67], v[62:63]
	v_cvt_f32_f16_e32 v60, v48
	v_pk_add_f32 v[62:63], v[62:63], v[62:63] op_sel_hi:[0,1]
	v_cvt_f32_f16_sdwa v62, v49 dst_sel:DWORD dst_unused:UNUSED_PAD src0_sel:WORD_1
	v_cvt_f32_f16_e32 v66, v49
	v_add_f32_e32 v67, v60, v59
	v_cvt_f32_f16_sdwa v60, v47 dst_sel:DWORD dst_unused:UNUSED_PAD src0_sel:WORD_1
	s_and_b64 s[2:3], exec, s[38:39]
	v_add_f32_e32 v69, v66, v62
	v_cvt_f32_f16_e32 v66, v46
	v_cvt_f32_f16_e32 v62, v47
	s_or_b64 s[22:23], s[2:3], s[22:23]
	v_pk_add_f32 v[66:67], v[66:67], v[68:69]
	v_pk_add_f32 v[60:61], v[62:63], v[60:61]
	s_nop 0
	v_pk_add_f32 v[60:61], v[66:67], v[60:61]
	s_nop 0
	v_add_f32_e32 v59, v60, v61
	ds_bpermute_b32 v60, v33, v59
	s_waitcnt lgkmcnt(0)
	v_add_f32_e32 v59, v59, v60
	ds_bpermute_b32 v60, v54, v59
	s_waitcnt lgkmcnt(0)
	v_add_f32_e32 v59, v59, v60
	s_nop 1
	v_add_f32_dpp v59, v59, v59 quad_perm:[1,0,3,2] row_mask:0xf bank_mask:0xf
	s_nop 1
	v_add_f32_dpp v59, v59, v59 quad_perm:[2,3,0,1] row_mask:0xf bank_mask:0xf
	s_nop 1
	v_add_f32_dpp v59, v59, v59 row_half_mirror row_mask:0xf bank_mask:0xf
	s_nop 1
	v_add_f32_dpp v59, v59, v59 row_mirror row_mask:0xf bank_mask:0xf
	v_fma_mix_f32 v61, v59, s65, v52 op_sel:[0,0,1] op_sel_hi:[0,0,1]
	v_fma_mix_f32 v60, v59, s65, v52 op_sel_hi:[0,0,1]
	v_fma_mix_f32 v63, v59, s65, v53 op_sel:[0,0,1] op_sel_hi:[0,0,1]
	v_fma_mix_f32 v62, v59, s65, v53 op_sel_hi:[0,0,1]
	v_pk_mul_f32 v[52:53], v[62:63], v[62:63]
	v_pk_mul_f32 v[66:67], v[60:61], v[60:61]
	v_fma_mix_f32 v77, v59, s65, v47 op_sel:[0,0,1] op_sel_hi:[0,0,1]
	v_pk_mov_b32 v[68:69], v[66:67], v[52:53] op_sel:[1,0]
	v_mov_b32_e32 v67, v53
	v_pk_add_f32 v[52:53], v[68:69], v[66:67]
	v_fma_mix_f32 v67, v59, s65, v50 op_sel:[0,0,1] op_sel_hi:[0,0,1]
	v_fma_mix_f32 v66, v59, s65, v50 op_sel_hi:[0,0,1]
	v_fma_mix_f32 v69, v59, s65, v51 op_sel:[0,0,1] op_sel_hi:[0,0,1]
	v_fma_mix_f32 v68, v59, s65, v51 op_sel_hi:[0,0,1]
	v_pk_mul_f32 v[50:51], v[68:69], v[68:69]
	v_pk_mul_f32 v[70:71], v[66:67], v[66:67]
	v_pk_add_f32 v[52:53], v[52:53], v[52:53] op_sel_hi:[0,1]
	v_pk_mov_b32 v[72:73], v[70:71], v[50:51] op_sel:[1,0]
	v_mov_b32_e32 v71, v51
	v_pk_add_f32 v[50:51], v[72:73], v[70:71]
	v_fma_mix_f32 v70, v59, s65, v48 op_sel_hi:[0,0,1]
	v_fma_mix_f32 v71, v59, s65, v48 op_sel:[0,0,1] op_sel_hi:[0,0,1]
	v_mul_f32_e32 v48, v70, v70
	v_fma_mix_f32 v73, v59, s65, v49 op_sel:[0,0,1] op_sel_hi:[0,0,1]
	v_fma_mix_f32 v72, v59, s65, v49 op_sel_hi:[0,0,1]
	v_pk_fma_f32 v[48:49], v[70:71], v[70:71], v[48:49] op_sel_hi:[1,1,0]
	v_pk_add_f32 v[50:51], v[50:51], v[50:51] op_sel_hi:[0,1]
	v_mul_f32_e32 v48, v72, v72
	v_pk_fma_f32 v[74:75], v[72:73], v[72:73], v[48:49] op_sel_hi:[1,1,0]
	v_fma_mix_f32 v76, v59, s65, v47 op_sel_hi:[0,0,1]
	v_fma_mix_f32 v47, v59, s65, v46 op_sel:[0,0,1] op_sel_hi:[0,0,1]
	v_fma_mix_f32 v46, v59, s65, v46 op_sel_hi:[0,0,1]
	v_mul_f32_e32 v48, v46, v46
	v_mul_f32_e32 v74, v47, v47
	v_mul_f32_e32 v52, v76, v76
	v_mul_f32_e32 v50, v77, v77
	v_pk_add_f32 v[48:49], v[48:49], v[74:75]
	v_pk_add_f32 v[50:51], v[52:53], v[50:51]
	s_nop 0
	v_pk_add_f32 v[48:49], v[48:49], v[50:51]
	s_nop 0
	v_add_f32_e32 v48, v48, v49
	ds_bpermute_b32 v49, v33, v48
	s_waitcnt lgkmcnt(0)
; DI unsigned pk_bf16(float lo, float hi) { f32x2_t v = {lo, hi}; return __builtin_bit_cast(unsigned, __builtin_convertvector(v, bf16x2_t)); }
; DI float shfl_xor_l(float v, int mask, int lane) { return __int_as_float(__builtin_amdgcn_ds_bpermute((lane ^ mask) << 2, __float_as_int(v))); }
; DI void ln_phase(const Params& p, const u16* src, const float* g, const float* b, float* dstf, u16* dstb) {
;     ...
;     for (int o = 32; o >= 1; o >>= 1) q += shfl_xor_l(q, o, lane);
;     const float rstd = 1.0f / sqrtf(q * (1.0f / 1024.0f) + 1e-5f);
; #pragma unroll
;     for (int i = 0; i < 4; ++i) {
;       const int col = i * 256 + lane * 4;
;       const f32x4 o = v[i] * rstd * gv[i] + bv[i];
;       if (dstf) *(f32x4*)(dstf + (size_t)row * D + col) = o;
;       if (dstb) { u32x2 ob; ob[0] = pk_bf16(o[0], o[1]); ob[1] = pk_bf16(o[2], o[3]); *(u32x2*)(dstb + (size_t)row * D + col) = ob; }
;     }
; #pragma unroll
;     for (int i = 0; i < 4; ++i) raw[i] = nxt[i];
;   }
	v_add_f32_e32 v48, v48, v49
	ds_bpermute_b32 v49, v54, v48
	s_waitcnt lgkmcnt(0)
	v_add_f32_e32 v48, v48, v49
	s_nop 1
	v_add_f32_dpp v48, v48, v48 quad_perm:[1,0,3,2] row_mask:0xf bank_mask:0xf
	s_nop 1
	v_add_f32_dpp v48, v48, v48 quad_perm:[2,3,0,1] row_mask:0xf bank_mask:0xf
	s_nop 1
	v_add_f32_dpp v48, v48, v48 row_half_mirror row_mask:0xf bank_mask:0xf
	s_nop 1
	v_add_f32_dpp v48, v48, v48 row_mirror row_mask:0xf bank_mask:0xf
	v_mov_b32_e32 v49, 0x3727c5ac
	v_fmamk_f32 v48, v48, 0x3a800000, v49
	v_cmp_gt_f32_e32 vcc, s66, v48
	v_mul_f32_e32 v49, 0x4f800000, v48
	s_nop 0
	v_cndmask_b32_e32 v48, v48, v49, vcc
	v_sqrt_f32_e32 v49, v48
	s_nop 0
	v_add_u32_e32 v50, -1, v49
	v_fma_f32 v51, -v50, v49, v48
	v_cmp_ge_f32_e64 s[38:39], 0, v51
	v_add_u32_e32 v51, 1, v49
	s_nop 0
	v_cndmask_b32_e64 v50, v49, v50, s[38:39]
	v_fma_f32 v49, -v51, v49, v48
	v_cmp_lt_f32_e64 s[38:39], 0, v49
	s_nop 1
	v_cndmask_b32_e64 v49, v50, v51, s[38:39]
	v_mul_f32_e32 v50, 0x37800000, v49
	v_cndmask_b32_e32 v49, v49, v50, vcc
	v_mov_b32_e32 v50, 0x260
	v_cmp_class_f32_e32 vcc, v48, v50
	s_nop 1
	v_cndmask_b32_e32 v48, v49, v48, vcc
	v_div_scale_f32 v49, s[2:3], v48, v48, 1.0
	v_rcp_f32_e32 v50, v49
	s_mov_b32 s2, 0xaa80000
	v_fma_f32 v51, -v49, v50, 1.0
	v_fmac_f32_e32 v50, v51, v50
	v_div_scale_f32 v51, vcc, 1.0, v48, 1.0
	v_mul_f32_e32 v52, v51, v50
	v_fma_f32 v53, -v49, v52, v51
	v_fmac_f32_e32 v52, v53, v50
	v_fma_f32 v49, -v49, v52, v51
	v_div_fmas_f32 v49, v49, v50, v52
	v_div_fixup_f32 v48, v49, v48, 1.0
	v_pk_mul_f32 v[50:51], v[60:61], v[48:49] op_sel_hi:[1,0]
	v_pk_mul_f32 v[52:53], v[62:63], v[48:49] op_sel_hi:[1,0]
	v_pk_fma_f32 v[50:51], v[0:1], v[50:51], v[8:9]
	v_pk_fma_f32 v[52:53], v[2:3], v[52:53], v[10:11]
	v_cvt_pk_bf16_f32 v50, v50, v51
	v_cvt_pk_bf16_f32 v51, v52, v53
	v_lshl_add_u64 v[52:53], v[34:35], 0, v[64:65]
	v_add_co_u32_e32 v52, vcc, s2, v52
	v_pk_mul_f32 v[60:61], v[68:69], v[48:49] op_sel_hi:[1,0]
	s_nop 0
	v_addc_co_u32_e32 v53, vcc, 0, v53, vcc
	global_store_dwordx2 v[52:53], v[50:51], off
	v_pk_mul_f32 v[50:51], v[66:67], v[48:49] op_sel_hi:[1,0]
	v_pk_fma_f32 v[60:61], v[6:7], v[60:61], v[14:15]
	v_pk_fma_f32 v[50:51], v[4:5], v[50:51], v[12:13]
	v_pk_mul_f32 v[46:47], v[46:47], v[48:49] op_sel_hi:[1,0]
	v_cvt_pk_bf16_f32 v50, v50, v51
	v_cvt_pk_bf16_f32 v51, v60, v61
	global_store_dwordx2 v[52:53], v[50:51], off offset:512
	v_pk_mul_f32 v[50:51], v[70:71], v[48:49] op_sel_hi:[1,0]
	v_pk_mul_f32 v[60:61], v[72:73], v[48:49] op_sel_hi:[1,0]
	v_pk_mul_f32 v[48:49], v[76:77], v[48:49] op_sel_hi:[1,0]
	v_pk_fma_f32 v[60:61], v[18:19], v[60:61], v[26:27]
	v_pk_fma_f32 v[50:51], v[16:17], v[50:51], v[24:25]
	v_pk_fma_f32 v[48:49], v[22:23], v[48:49], v[30:31]
	v_pk_fma_f32 v[46:47], v[20:21], v[46:47], v[28:29]
	v_readlane_b32 s2, v255, 14
	v_cvt_pk_bf16_f32 v50, v50, v51
	v_cvt_pk_bf16_f32 v51, v60, v61
	v_cvt_pk_bf16_f32 v46, v46, v47
	v_cvt_pk_bf16_f32 v47, v48, v49
	v_readlane_b32 s3, v255, 15
	global_store_dwordx2 v[52:53], v[50:51], off offset:1024
	global_store_dwordx2 v[52:53], v[46:47], off offset:1536
	v_lshl_add_u64 v[34:35], v[34:35], 0, s[2:3]
	v_lshl_add_u64 v[36:37], v[36:37], 0, s[2:3]
	v_mov_b32_e32 v52, v38
	v_mov_b32_e32 v53, v39
	v_mov_b32_e32 v50, v40
	v_mov_b32_e32 v51, v41
	v_mov_b32_e32 v48, v42
	v_mov_b32_e32 v49, v43
	v_mov_b32_e32 v46, v44
	v_mov_b32_e32 v47, v45
	s_andn2_b64 exec, exec, s[22:23]
	s_cbranch_execz .LBB0_1114

; DI float h2lo(unsigned u) { return (float)__builtin_bit_cast(f16x2_t, u)[0]; }
; DI float h2hi(unsigned u) { return (float)__builtin_bit_cast(f16x2_t, u)[1]; }
; DI float shfl_xor_l(float v, int mask, int lane) { return __int_as_float(__builtin_amdgcn_ds_bpermute((lane ^ mask) << 2, __float_as_int(v))); }
; DI void ln_phase(const Params& p, const u16* src, const float* g, const float* b, float* dstf, u16* dstb) {
;     ...
;     for (int i = 0; i < 4; ++i) { v[i] = (f32x4){h2lo(raw[i][0]), h2hi(raw[i][0]), h2lo(raw[i][1]), h2hi(raw[i][1])}; s += (v[i][0] + v[i][1]) + (v[i][2] + v[i][3]); }
; #pragma unroll
;     for (int o = 32; o >= 1; o >>= 1) s += shfl_xor_l(s, o, lane);
;     const float mu = s * (1.0f / 1024.0f);
;     float q = 0.f;
; #pragma unroll
;     for (int i = 0; i < 4; ++i) { v[i] = v[i] - mu; q += (v[i][0] * v[i][0] + v[i][1] * v[i][1]) + (v[i][2] * v[i][2] + v[i][3] * v[i][3]); }
; #pragma unroll
;     for (int o = 32; o >= 1; o >>= 1) q += shfl_xor_l(q, o, lane);
;     const float rstd = 1.0f / sqrtf(q * (1.0f / 1024.0f) + 1e-5f);
; #pragma unroll
;     for (int i = 0; i < 4; ++i) {
;       const int col = i * 256 + lane * 4;
;       const f32x4 o = v[i] * rstd * gv[i] + bv[i];
;       if (dstf) *(f32x4*)(dstf + (size_t)row * D + col) = o;
.LBB0_1327:
	s_or_b64 exec, exec, s[38:39]
	s_waitcnt vmcnt(3)
	v_cvt_f32_f16_sdwa v56, v54 dst_sel:DWORD dst_unused:UNUSED_PAD src0_sel:WORD_1
	v_cvt_f32_f16_e32 v58, v54
	v_cvt_f32_f16_sdwa v57, v55 dst_sel:DWORD dst_unused:UNUSED_PAD src0_sel:WORD_1
	v_cvt_f32_f16_e32 v59, v55
	s_waitcnt vmcnt(2)
	v_cvt_f32_f16_sdwa v60, v52 dst_sel:DWORD dst_unused:UNUSED_PAD src0_sel:WORD_1
	v_cvt_f32_f16_e32 v62, v52
	v_cvt_f32_f16_sdwa v61, v53 dst_sel:DWORD dst_unused:UNUSED_PAD src0_sel:WORD_1
	v_cvt_f32_f16_e32 v63, v53
	v_pk_add_f32 v[56:57], v[58:59], v[56:57]
	s_waitcnt vmcnt(1)
	v_cvt_f32_f16_sdwa v66, v35 dst_sel:DWORD dst_unused:UNUSED_PAD src0_sel:WORD_1
	v_add_f32_e32 v37, v56, v57
	v_pk_add_f32 v[58:59], v[62:63], v[60:61]
	v_add_f32_e32 v57, 0, v37
	v_pk_add_f32 v[58:59], v[58:59], v[58:59] op_sel_hi:[0,1]
	v_cvt_f32_f16_sdwa v37, v34 dst_sel:DWORD dst_unused:UNUSED_PAD src0_sel:WORD_1
	v_cvt_f32_f16_e32 v61, v34
	v_cvt_f32_f16_e32 v67, v35
	s_waitcnt vmcnt(0)
	v_cvt_f32_f16_sdwa v60, v32 dst_sel:DWORD dst_unused:UNUSED_PAD src0_sel:WORD_1
	v_cvt_f32_f16_e32 v62, v32
	v_cvt_f32_f16_sdwa v56, v33 dst_sel:DWORD dst_unused:UNUSED_PAD src0_sel:WORD_1
	v_cvt_f32_f16_e32 v58, v33
	v_add_f32_e32 v63, v61, v37
	v_add_f32_e32 v61, v67, v66
	v_pk_add_f32 v[60:61], v[62:63], v[60:61]
	v_pk_add_f32 v[56:57], v[58:59], v[56:57]
	s_nop 0
	v_pk_add_f32 v[56:57], v[60:61], v[56:57]
	s_nop 0
	v_add_f32_e32 v37, v56, v57
	ds_bpermute_b32 v56, v70, v37
	s_waitcnt lgkmcnt(0)
	v_add_f32_e32 v37, v37, v56
	ds_bpermute_b32 v56, v71, v37
	s_waitcnt lgkmcnt(0)
	v_add_f32_e32 v37, v37, v56
	s_nop 1
	v_add_f32_dpp v37, v37, v37 quad_perm:[1,0,3,2] row_mask:0xf bank_mask:0xf
	s_nop 1
	v_add_f32_dpp v37, v37, v37 quad_perm:[2,3,0,1] row_mask:0xf bank_mask:0xf
	s_nop 1
	v_add_f32_dpp v37, v37, v37 row_half_mirror row_mask:0xf bank_mask:0xf
	s_nop 1
	v_add_f32_dpp v37, v37, v37 row_mirror row_mask:0xf bank_mask:0xf
	v_fma_mix_f32 v67, v37, s65, v54 op_sel:[0,0,1] op_sel_hi:[0,0,1]
	v_fma_mix_f32 v66, v37, s65, v54 op_sel_hi:[0,0,1]
	v_fma_mix_f32 v77, v37, s65, v55 op_sel:[0,0,1] op_sel_hi:[0,0,1]
	v_fma_mix_f32 v76, v37, s65, v55 op_sel_hi:[0,0,1]
	v_fma_mix_f32 v61, v37, s65, v53 op_sel:[0,0,1] op_sel_hi:[0,0,1]
	v_fma_mix_f32 v60, v37, s65, v53 op_sel_hi:[0,0,1]
	v_fma_mix_f32 v63, v37, s65, v52 op_sel:[0,0,1] op_sel_hi:[0,0,1]
	v_fma_mix_f32 v62, v37, s65, v52 op_sel_hi:[0,0,1]
	v_pk_mul_f32 v[52:53], v[76:77], v[76:77]
	v_pk_mul_f32 v[54:55], v[66:67], v[66:67]
	v_pk_mul_f32 v[56:57], v[60:61], v[60:61]
	v_pk_mov_b32 v[58:59], v[54:55], v[52:53] op_sel:[1,0]
	v_mov_b32_e32 v55, v53
	v_pk_add_f32 v[52:53], v[58:59], v[54:55]
	v_fma_mix_f32 v58, v37, s65, v34 op_sel_hi:[0,0,1]
	v_pk_add_f32 v[68:69], v[52:53], v[52:53] op_sel_hi:[0,1]
	v_pk_mul_f32 v[52:53], v[62:63], v[62:63]
	v_fma_mix_f32 v59, v37, s65, v34 op_sel:[0,0,1] op_sel_hi:[0,0,1]
	v_mul_f32_e32 v34, v58, v58
	v_pk_mov_b32 v[54:55], v[52:53], v[56:57] op_sel:[1,0]
	v_mov_b32_e32 v53, v57
	v_fma_mix_f32 v57, v37, s65, v35 op_sel:[0,0,1] op_sel_hi:[0,0,1]
	v_fma_mix_f32 v56, v37, s65, v35 op_sel_hi:[0,0,1]
	v_pk_fma_f32 v[34:35], v[58:59], v[58:59], v[34:35] op_sel_hi:[1,1,0]
	v_pk_add_f32 v[52:53], v[54:55], v[52:53]
	v_mul_f32_e32 v34, v56, v56
	v_pk_add_f32 v[78:79], v[52:53], v[52:53] op_sel_hi:[0,1]
	v_pk_fma_f32 v[80:81], v[56:57], v[56:57], v[34:35] op_sel_hi:[1,1,0]
	v_fma_mix_f32 v53, v37, s65, v33 op_sel:[0,0,1] op_sel_hi:[0,0,1]
	v_fma_mix_f32 v52, v37, s65, v33 op_sel_hi:[0,0,1]
	v_fma_mix_f32 v55, v37, s65, v32 op_sel:[0,0,1] op_sel_hi:[0,0,1]
	v_fma_mix_f32 v54, v37, s65, v32 op_sel_hi:[0,0,1]
	v_mul_f32_e32 v34, v54, v54
	v_mul_f32_e32 v80, v55, v55
	v_mul_f32_e32 v68, v52, v52
	v_mul_f32_e32 v78, v53, v53
	v_pk_add_f32 v[32:33], v[34:35], v[80:81]
	v_pk_add_f32 v[34:35], v[68:69], v[78:79]
	s_nop 0
	v_pk_add_f32 v[32:33], v[32:33], v[34:35]
	s_nop 0
	v_add_f32_e32 v32, v32, v33
	ds_bpermute_b32 v33, v70, v32
	s_waitcnt lgkmcnt(0)
	v_add_f32_e32 v32, v32, v33
	ds_bpermute_b32 v33, v71, v32
	s_waitcnt lgkmcnt(0)
	v_add_f32_e32 v32, v32, v33
	s_nop 1
	v_add_f32_dpp v32, v32, v32 quad_perm:[1,0,3,2] row_mask:0xf bank_mask:0xf
	s_nop 1
	v_add_f32_dpp v32, v32, v32 quad_perm:[2,3,0,1] row_mask:0xf bank_mask:0xf
	s_nop 1
	v_add_f32_dpp v32, v32, v32 row_half_mirror row_mask:0xf bank_mask:0xf
	s_nop 1
	v_add_f32_dpp v32, v32, v32 row_mirror row_mask:0xf bank_mask:0xf
	v_mov_b32_e32 v33, 0x3727c5ac
	v_fmamk_f32 v32, v32, 0x3a800000, v33
	v_mul_f32_e32 v33, 0x4f800000, v32
	v_cmp_gt_f32_e32 vcc, s66, v32
	s_nop 1
	v_cndmask_b32_e32 v32, v32, v33, vcc
	v_sqrt_f32_e32 v33, v32
	s_nop 0
	v_add_u32_e32 v34, -1, v33
	v_add_u32_e32 v35, 1, v33
	v_fma_f32 v37, -v34, v33, v32
	v_fma_f32 v68, -v35, v33, v32
	v_cmp_ge_f32_e64 s[38:39], 0, v37
	s_nop 1
	v_cndmask_b32_e64 v33, v33, v34, s[38:39]
	v_cmp_lt_f32_e64 s[38:39], 0, v68
	s_nop 1
	v_cndmask_b32_e64 v33, v33, v35, s[38:39]
	v_mul_f32_e32 v34, 0x37800000, v33
	v_cndmask_b32_e32 v33, v33, v34, vcc
	v_mov_b32_e32 v34, 0x260
	v_cmp_class_f32_e32 vcc, v32, v34
	s_nop 1
	v_cndmask_b32_e32 v32, v33, v32, vcc
	v_div_scale_f32 v33, s[2:3], v32, v32, 1.0
	v_rcp_f32_e32 v34, v33
	v_div_scale_f32 v35, vcc, 1.0, v32, 1.0
	v_fma_f32 v37, -v33, v34, 1.0
	v_fmac_f32_e32 v34, v37, v34
	v_mul_f32_e32 v37, v35, v34
	v_fma_f32 v68, -v33, v37, v35
	v_fmac_f32_e32 v37, v68, v34
	v_fma_f32 v33, -v33, v37, v35
	v_div_fmas_f32 v33, v33, v34, v37
	v_div_fixup_f32 v68, v33, v32, 1.0
	v_pk_mul_f32 v[32:33], v[66:67], v[68:69] op_sel_hi:[1,0]
	v_pk_mul_f32 v[34:35], v[76:77], v[68:69] op_sel_hi:[1,0]
	v_cndmask_b32_e64 v37, 0, 1, s[28:29]
	v_pk_fma_f32 v[34:35], v[2:3], v[34:35], v[10:11]
	v_cmp_ne_u32_e64 s[38:39], 1, v37
	s_andn2_b64 vcc, exec, s[28:29]
	v_pk_fma_f32 v[32:33], v[0:1], v[32:33], v[8:9]
	s_cbranch_vccnz .LBB0_1329
	global_store_dwordx4 v[42:43], v[32:35], off offset:-2048
